# v017 + p2b item-top waits no longer drain the previous item's kvT stores (one drain before the loop, single vmcnt(8) inside)
# baseline (speedup 1.0000x reference)
.LBB0_269:
	s_cmpk_gt_i32 s60, 0x1ff
	s_cbranch_scc1 .LBB0_276
	s_mov_b32 s6, 0x979a371
	s_waitcnt vmcnt(34)
	v_cvt_f64_u32_e32 v[0:1], v40
	s_mov_b32 s7, 0xbfca934f
	s_waitcnt vmcnt(32)
	v_mul_f64 v[2:3], v[0:1], s[6:7]
	s_waitcnt vmcnt(14)
	v_rndne_f64_e32 v[4:5], v[2:3]
	s_mov_b32 s12, 0x3b39803f
	v_add_f64 v[0:1], v[2:3], -v[4:5]
	s_mov_b32 s13, 0x3c7abc9e
	s_mov_b32 s20, 0xfefa39ef
	s_mov_b32 s0, 0xfca7ab0c
	v_mul_f64 v[6:7], v[0:1], s[12:13]
	s_mov_b32 s21, 0x3fe62e42
	s_mov_b32 s1, 0x3e928af3
	s_mov_b32 s22, 0x6a5dcb37
	v_fmac_f64_e32 v[6:7], s[20:21], v[0:1]
	s_mov_b32 s23, 0x3e5ade15
	v_mov_b64_e32 v[0:1], s[0:1]
	s_mov_b32 s24, 0x623fde64
	s_waitcnt vmcnt(13)
	v_fma_f64 v[8:9], s[22:23], v[6:7], v[0:1]
	s_mov_b32 s25, 0x3ec71dee
	s_mov_b32 s26, 0x7c89e6b0
	v_fma_f64 v[8:9], v[6:7], v[8:9], s[24:25]
	s_mov_b32 s27, 0x3efa0199
	s_mov_b32 s28, 0x14761f6e
	v_fma_f64 v[8:9], v[6:7], v[8:9], s[26:27]
	s_mov_b32 s29, 0x3f2a01a0
	s_mov_b32 s30, 0x1852b7b0
	v_fma_f64 v[8:9], v[6:7], v[8:9], s[28:29]
	s_mov_b32 s31, 0x3f56c16c
	s_mov_b32 s34, 0x11122322
	v_fma_f64 v[8:9], v[6:7], v[8:9], s[30:31]
	s_mov_b32 s35, 0x3f811111
	s_mov_b32 s36, 0x555502a1
	v_fma_f64 v[8:9], v[6:7], v[8:9], s[34:35]
	s_mov_b32 s37, 0x3fa55555
	s_mov_b32 s38, 0x55555511
	v_fma_f64 v[8:9], v[6:7], v[8:9], s[36:37]
	s_mov_b32 s39, 0x3fc55555
	s_mov_b32 s40, 11
	v_fma_f64 v[8:9], v[6:7], v[8:9], s[38:39]
	s_mov_b32 s41, 0x3fe00000
	v_fma_f64 v[8:9], v[6:7], v[8:9], s[40:41]
	v_fma_f64 v[8:9], v[6:7], v[8:9], 1.0
	v_fma_f64 v[6:7], v[6:7], v[8:9], 1.0
	v_cvt_i32_f64_e32 v4, v[4:5]
	s_mov_b32 s4, 0x6dc9c883
	s_mov_b32 s10, 0
	s_mov_b32 s16, 0
	v_ldexp_f64 v[4:5], v[6:7], v4
	s_mov_b32 s5, 0x3fc45f30
	s_mov_b32 s11, 0x40900000
	s_mov_b32 s17, 0xc090cc00
	v_mul_f64 v[4:5], v[4:5], s[4:5]
	s_waitcnt vmcnt(5)
	v_mov_b32_e32 v70, 0x7ff00000
	v_cmp_nlt_f64_e32 vcc, s[10:11], v[2:3]
	v_cmp_ngt_f64_e64 s[0:1], s[16:17], v[2:3]
	v_or_b32_e32 v90, 32, v40
	v_cndmask_b32_e32 v5, v70, v5, vcc
	s_and_b64 vcc, s[0:1], vcc
	v_cndmask_b32_e64 v3, 0, v5, s[0:1]
	v_cndmask_b32_e32 v2, 0, v4, vcc
	v_cvt_f32_f64_e32 v55, v[2:3]
	v_cvt_f64_f32_e32 v[4:5], v55
	v_add_f64 v[32:33], v[2:3], -v[4:5]
	v_or_b32_e32 v2, 1, v40
	v_cvt_f64_u32_e32 v[2:3], v2
	v_mul_f64 v[2:3], v[2:3], s[6:7]
	v_rndne_f64_e32 v[4:5], v[2:3]
	v_add_f64 v[6:7], v[2:3], -v[4:5]
	v_mul_f64 v[8:9], v[6:7], s[12:13]
	v_fmac_f64_e32 v[8:9], s[20:21], v[6:7]
	v_fma_f64 v[6:7], s[22:23], v[8:9], v[0:1]
	v_fma_f64 v[6:7], v[8:9], v[6:7], s[24:25]
	v_fma_f64 v[6:7], v[8:9], v[6:7], s[26:27]
	v_fma_f64 v[6:7], v[8:9], v[6:7], s[28:29]
	v_fma_f64 v[6:7], v[8:9], v[6:7], s[30:31]
	v_fma_f64 v[6:7], v[8:9], v[6:7], s[34:35]
	v_fma_f64 v[6:7], v[8:9], v[6:7], s[36:37]
	v_fma_f64 v[6:7], v[8:9], v[6:7], s[38:39]
	v_fma_f64 v[6:7], v[8:9], v[6:7], s[40:41]
	v_fma_f64 v[6:7], v[8:9], v[6:7], 1.0
	v_fma_f64 v[6:7], v[8:9], v[6:7], 1.0
	v_cvt_i32_f64_e32 v4, v[4:5]
	v_ldexp_f64 v[4:5], v[6:7], v4
	v_mul_f64 v[4:5], v[4:5], s[4:5]
	v_cmp_nlt_f64_e32 vcc, s[10:11], v[2:3]
	v_cmp_ngt_f64_e64 s[0:1], s[16:17], v[2:3]
	s_movk_i32 s2, 0x3000
	v_cndmask_b32_e32 v5, v70, v5, vcc
	s_and_b64 vcc, s[0:1], vcc
	v_cndmask_b32_e64 v3, 0, v5, s[0:1]
	v_cndmask_b32_e32 v2, 0, v4, vcc
	v_cvt_f32_f64_e32 v56, v[2:3]
	v_cvt_f64_f32_e32 v[4:5], v56
	v_add_f64 v[34:35], v[2:3], -v[4:5]
	v_or_b32_e32 v2, 2, v40
	v_cvt_f64_u32_e32 v[2:3], v2
	v_mul_f64 v[2:3], v[2:3], s[6:7]
	v_rndne_f64_e32 v[4:5], v[2:3]
	v_add_f64 v[6:7], v[2:3], -v[4:5]
	v_mul_f64 v[8:9], v[6:7], s[12:13]
	v_fmac_f64_e32 v[8:9], s[20:21], v[6:7]
	v_fma_f64 v[6:7], s[22:23], v[8:9], v[0:1]
	v_fma_f64 v[6:7], v[8:9], v[6:7], s[24:25]
	v_fma_f64 v[6:7], v[8:9], v[6:7], s[26:27]
	v_fma_f64 v[6:7], v[8:9], v[6:7], s[28:29]
	v_fma_f64 v[6:7], v[8:9], v[6:7], s[30:31]
	v_fma_f64 v[6:7], v[8:9], v[6:7], s[34:35]
	v_fma_f64 v[6:7], v[8:9], v[6:7], s[36:37]
	v_fma_f64 v[6:7], v[8:9], v[6:7], s[38:39]
	v_fma_f64 v[6:7], v[8:9], v[6:7], s[40:41]
	v_fma_f64 v[6:7], v[8:9], v[6:7], 1.0
	v_fma_f64 v[6:7], v[8:9], v[6:7], 1.0
	v_cvt_i32_f64_e32 v4, v[4:5]
	v_ldexp_f64 v[4:5], v[6:7], v4
	v_mul_f64 v[4:5], v[4:5], s[4:5]
	v_cmp_nlt_f64_e32 vcc, s[10:11], v[2:3]
	v_cmp_ngt_f64_e64 s[0:1], s[16:17], v[2:3]
	s_mov_b32 s19, 0
	v_cndmask_b32_e32 v5, v70, v5, vcc
	s_and_b64 vcc, s[0:1], vcc
	v_cndmask_b32_e64 v3, 0, v5, s[0:1]
	v_cndmask_b32_e32 v2, 0, v4, vcc
	v_cvt_f32_f64_e32 v57, v[2:3]
	v_cvt_f64_f32_e32 v[4:5], v57
	s_waitcnt vmcnt(4)
	v_add_f64 v[36:37], v[2:3], -v[4:5]
	v_or_b32_e32 v2, 3, v40
	v_cvt_f64_u32_e32 v[2:3], v2
	v_mul_f64 v[2:3], v[2:3], s[6:7]
	v_rndne_f64_e32 v[4:5], v[2:3]
	v_add_f64 v[6:7], v[2:3], -v[4:5]
	v_mul_f64 v[8:9], v[6:7], s[12:13]
	v_fmac_f64_e32 v[8:9], s[20:21], v[6:7]
	v_fma_f64 v[6:7], s[22:23], v[8:9], v[0:1]
	v_fma_f64 v[6:7], v[8:9], v[6:7], s[24:25]
	v_fma_f64 v[6:7], v[8:9], v[6:7], s[26:27]
	v_fma_f64 v[6:7], v[8:9], v[6:7], s[28:29]
	v_fma_f64 v[6:7], v[8:9], v[6:7], s[30:31]
	v_fma_f64 v[6:7], v[8:9], v[6:7], s[34:35]
	v_fma_f64 v[6:7], v[8:9], v[6:7], s[36:37]
	v_fma_f64 v[6:7], v[8:9], v[6:7], s[38:39]
	v_fma_f64 v[6:7], v[8:9], v[6:7], s[40:41]
	v_fma_f64 v[6:7], v[8:9], v[6:7], 1.0
	v_fma_f64 v[6:7], v[8:9], v[6:7], 1.0
	v_cvt_i32_f64_e32 v4, v[4:5]
	v_ldexp_f64 v[4:5], v[6:7], v4
	v_mul_f64 v[4:5], v[4:5], s[4:5]
	v_cmp_nlt_f64_e32 vcc, s[10:11], v[2:3]
	v_cmp_ngt_f64_e64 s[0:1], s[16:17], v[2:3]
	v_mov_b32_e32 v41, 0
	v_cndmask_b32_e32 v5, v70, v5, vcc
	s_and_b64 vcc, s[0:1], vcc
	v_cndmask_b32_e64 v3, 0, v5, s[0:1]
	v_cndmask_b32_e32 v2, 0, v4, vcc
	v_cvt_f32_f64_e32 v58, v[2:3]
	v_cvt_f64_f32_e32 v[4:5], v58
	v_add_f64 v[38:39], v[2:3], -v[4:5]
	v_or_b32_e32 v2, 4, v40
	v_cvt_f64_u32_e32 v[2:3], v2
	v_mul_f64 v[2:3], v[2:3], s[6:7]
	v_rndne_f64_e32 v[4:5], v[2:3]
	v_add_f64 v[6:7], v[2:3], -v[4:5]
	v_mul_f64 v[8:9], v[6:7], s[12:13]
	v_fmac_f64_e32 v[8:9], s[20:21], v[6:7]
	v_fma_f64 v[6:7], s[22:23], v[8:9], v[0:1]
	v_fma_f64 v[6:7], v[8:9], v[6:7], s[24:25]
	v_fma_f64 v[6:7], v[8:9], v[6:7], s[26:27]
	v_fma_f64 v[6:7], v[8:9], v[6:7], s[28:29]
	v_fma_f64 v[6:7], v[8:9], v[6:7], s[30:31]
	v_fma_f64 v[6:7], v[8:9], v[6:7], s[34:35]
	v_fma_f64 v[6:7], v[8:9], v[6:7], s[36:37]
	v_fma_f64 v[6:7], v[8:9], v[6:7], s[38:39]
	v_fma_f64 v[6:7], v[8:9], v[6:7], s[40:41]
	v_fma_f64 v[6:7], v[8:9], v[6:7], 1.0
	v_fma_f64 v[6:7], v[8:9], v[6:7], 1.0
	v_cvt_i32_f64_e32 v4, v[4:5]
	v_ldexp_f64 v[4:5], v[6:7], v4
	v_mul_f64 v[4:5], v[4:5], s[4:5]
	v_cmp_nlt_f64_e32 vcc, s[10:11], v[2:3]
	v_cmp_ngt_f64_e64 s[0:1], s[16:17], v[2:3]
	s_movk_i32 s3, 0x2000
	v_cndmask_b32_e32 v5, v70, v5, vcc
	s_and_b64 vcc, s[0:1], vcc
	v_cndmask_b32_e64 v3, 0, v5, s[0:1]
	v_cndmask_b32_e32 v2, 0, v4, vcc
	v_cvt_f32_f64_e32 v59, v[2:3]
	v_cvt_f64_f32_e32 v[4:5], v59
	v_add_f64 v[42:43], v[2:3], -v[4:5]
	v_or_b32_e32 v2, 5, v40
	v_cvt_f64_u32_e32 v[2:3], v2
	v_mul_f64 v[2:3], v[2:3], s[6:7]
	v_rndne_f64_e32 v[4:5], v[2:3]
	v_add_f64 v[6:7], v[2:3], -v[4:5]
	v_mul_f64 v[8:9], v[6:7], s[12:13]
	v_fmac_f64_e32 v[8:9], s[20:21], v[6:7]
	v_fma_f64 v[6:7], s[22:23], v[8:9], v[0:1]
	v_fma_f64 v[6:7], v[8:9], v[6:7], s[24:25]
	v_fma_f64 v[6:7], v[8:9], v[6:7], s[26:27]
	v_fma_f64 v[6:7], v[8:9], v[6:7], s[28:29]
	v_fma_f64 v[6:7], v[8:9], v[6:7], s[30:31]
	v_fma_f64 v[6:7], v[8:9], v[6:7], s[34:35]
	v_fma_f64 v[6:7], v[8:9], v[6:7], s[36:37]
	v_fma_f64 v[6:7], v[8:9], v[6:7], s[38:39]
	v_fma_f64 v[6:7], v[8:9], v[6:7], s[40:41]
	v_fma_f64 v[6:7], v[8:9], v[6:7], 1.0
	v_fma_f64 v[6:7], v[8:9], v[6:7], 1.0
	v_cvt_i32_f64_e32 v4, v[4:5]
	v_ldexp_f64 v[4:5], v[6:7], v4
	v_mul_f64 v[4:5], v[4:5], s[4:5]
	v_cmp_nlt_f64_e32 vcc, s[10:11], v[2:3]
	v_cmp_ngt_f64_e64 s[0:1], s[16:17], v[2:3]
	s_ashr_i32 s61, s60, 31
	v_cndmask_b32_e32 v5, v70, v5, vcc
	s_and_b64 vcc, s[0:1], vcc
	v_cndmask_b32_e64 v3, 0, v5, s[0:1]
	v_cndmask_b32_e32 v2, 0, v4, vcc
	v_cvt_f32_f64_e32 v60, v[2:3]
	v_cvt_f64_f32_e32 v[4:5], v60
	v_add_f64 v[44:45], v[2:3], -v[4:5]
	v_or_b32_e32 v2, 6, v40
	v_cvt_f64_u32_e32 v[2:3], v2
	v_mul_f64 v[2:3], v[2:3], s[6:7]
	v_rndne_f64_e32 v[4:5], v[2:3]
	v_add_f64 v[6:7], v[2:3], -v[4:5]
	v_mul_f64 v[8:9], v[6:7], s[12:13]
	v_fmac_f64_e32 v[8:9], s[20:21], v[6:7]
	v_fma_f64 v[6:7], s[22:23], v[8:9], v[0:1]
	v_fma_f64 v[6:7], v[8:9], v[6:7], s[24:25]
	v_fma_f64 v[6:7], v[8:9], v[6:7], s[26:27]
	v_fma_f64 v[6:7], v[8:9], v[6:7], s[28:29]
	v_fma_f64 v[6:7], v[8:9], v[6:7], s[30:31]
	v_fma_f64 v[6:7], v[8:9], v[6:7], s[34:35]
	v_fma_f64 v[6:7], v[8:9], v[6:7], s[36:37]
	v_fma_f64 v[6:7], v[8:9], v[6:7], s[38:39]
	v_fma_f64 v[6:7], v[8:9], v[6:7], s[40:41]
	v_fma_f64 v[6:7], v[8:9], v[6:7], 1.0
	v_fma_f64 v[6:7], v[8:9], v[6:7], 1.0
	v_cvt_i32_f64_e32 v4, v[4:5]
	v_ldexp_f64 v[4:5], v[6:7], v4
	v_mul_f64 v[4:5], v[4:5], s[4:5]
	v_cmp_nlt_f64_e32 vcc, s[10:11], v[2:3]
	v_cmp_ngt_f64_e64 s[0:1], s[16:17], v[2:3]
	v_cvt_f32_f64_e32 v44, v[44:45]
	v_cndmask_b32_e32 v5, v70, v5, vcc
	s_and_b64 vcc, s[0:1], vcc
	v_cndmask_b32_e64 v3, 0, v5, s[0:1]
	v_cndmask_b32_e32 v2, 0, v4, vcc
	v_cvt_f32_f64_e32 v61, v[2:3]
	v_cvt_f64_f32_e32 v[4:5], v61
	v_add_f64 v[46:47], v[2:3], -v[4:5]
	v_or_b32_e32 v2, 7, v40
	v_cvt_f64_u32_e32 v[2:3], v2
	v_mul_f64 v[2:3], v[2:3], s[6:7]
	v_rndne_f64_e32 v[4:5], v[2:3]
	v_add_f64 v[6:7], v[2:3], -v[4:5]
	v_mul_f64 v[8:9], v[6:7], s[12:13]
	v_fmac_f64_e32 v[8:9], s[20:21], v[6:7]
	v_fma_f64 v[6:7], s[22:23], v[8:9], v[0:1]
	v_fma_f64 v[6:7], v[8:9], v[6:7], s[24:25]
	v_fma_f64 v[6:7], v[8:9], v[6:7], s[26:27]
	v_fma_f64 v[6:7], v[8:9], v[6:7], s[28:29]
	v_fma_f64 v[6:7], v[8:9], v[6:7], s[30:31]
	v_fma_f64 v[6:7], v[8:9], v[6:7], s[34:35]
	v_fma_f64 v[6:7], v[8:9], v[6:7], s[36:37]
	v_fma_f64 v[6:7], v[8:9], v[6:7], s[38:39]
	v_fma_f64 v[6:7], v[8:9], v[6:7], s[40:41]
	v_fma_f64 v[6:7], v[8:9], v[6:7], 1.0
	v_fma_f64 v[6:7], v[8:9], v[6:7], 1.0
	v_cvt_i32_f64_e32 v4, v[4:5]
	v_ldexp_f64 v[4:5], v[6:7], v4
	v_mul_f64 v[4:5], v[4:5], s[4:5]
	v_cmp_nlt_f64_e32 vcc, s[10:11], v[2:3]
	v_cmp_ngt_f64_e64 s[0:1], s[16:17], v[2:3]
	v_cvt_f32_f64_e32 v45, v[46:47]
	v_cndmask_b32_e32 v5, v70, v5, vcc
	s_and_b64 vcc, s[0:1], vcc
	v_cndmask_b32_e64 v3, 0, v5, s[0:1]
	v_cndmask_b32_e32 v2, 0, v4, vcc
	v_cvt_f32_f64_e32 v62, v[2:3]
	v_cvt_f64_f32_e32 v[4:5], v62
	v_add_f64 v[48:49], v[2:3], -v[4:5]
	v_cvt_f64_u32_e32 v[2:3], v90
	v_mul_f64 v[2:3], v[2:3], s[6:7]
	v_rndne_f64_e32 v[4:5], v[2:3]
	v_add_f64 v[6:7], v[2:3], -v[4:5]
	v_mul_f64 v[8:9], v[6:7], s[12:13]
	v_fmac_f64_e32 v[8:9], s[20:21], v[6:7]
	v_fma_f64 v[6:7], s[22:23], v[8:9], v[0:1]
	v_fma_f64 v[6:7], v[8:9], v[6:7], s[24:25]
	v_fma_f64 v[6:7], v[8:9], v[6:7], s[26:27]
	v_fma_f64 v[6:7], v[8:9], v[6:7], s[28:29]
	v_fma_f64 v[6:7], v[8:9], v[6:7], s[30:31]
	v_fma_f64 v[6:7], v[8:9], v[6:7], s[34:35]
	v_fma_f64 v[6:7], v[8:9], v[6:7], s[36:37]
	v_fma_f64 v[6:7], v[8:9], v[6:7], s[38:39]
	v_fma_f64 v[6:7], v[8:9], v[6:7], s[40:41]
	v_fma_f64 v[6:7], v[8:9], v[6:7], 1.0
	v_fma_f64 v[6:7], v[8:9], v[6:7], 1.0
	v_cvt_i32_f64_e32 v4, v[4:5]
	v_ldexp_f64 v[4:5], v[6:7], v4
	v_mul_f64 v[4:5], v[4:5], s[4:5]
	v_cmp_nlt_f64_e32 vcc, s[10:11], v[2:3]
	v_cmp_ngt_f64_e64 s[0:1], s[16:17], v[2:3]
	v_cvt_f32_f64_e32 v46, v[48:49]
	v_cndmask_b32_e32 v5, v70, v5, vcc
	s_and_b64 vcc, s[0:1], vcc
	v_cndmask_b32_e64 v3, 0, v5, s[0:1]
	v_cndmask_b32_e32 v2, 0, v4, vcc
	v_cvt_f32_f64_e32 v63, v[2:3]
	v_cvt_f64_f32_e32 v[4:5], v63
	v_add_f64 v[50:51], v[2:3], -v[4:5]
	v_or_b32_e32 v2, 33, v40
	v_cvt_f64_u32_e32 v[2:3], v2
	v_mul_f64 v[2:3], v[2:3], s[6:7]
	v_rndne_f64_e32 v[4:5], v[2:3]
	v_add_f64 v[6:7], v[2:3], -v[4:5]
	v_mul_f64 v[8:9], v[6:7], s[12:13]
	v_fmac_f64_e32 v[8:9], s[20:21], v[6:7]
	v_fma_f64 v[6:7], s[22:23], v[8:9], v[0:1]
	v_fma_f64 v[6:7], v[8:9], v[6:7], s[24:25]
	v_fma_f64 v[6:7], v[8:9], v[6:7], s[26:27]
	v_fma_f64 v[6:7], v[8:9], v[6:7], s[28:29]
	v_fma_f64 v[6:7], v[8:9], v[6:7], s[30:31]
	v_fma_f64 v[6:7], v[8:9], v[6:7], s[34:35]
	v_fma_f64 v[6:7], v[8:9], v[6:7], s[36:37]
	v_fma_f64 v[6:7], v[8:9], v[6:7], s[38:39]
	v_fma_f64 v[6:7], v[8:9], v[6:7], s[40:41]
	v_fma_f64 v[6:7], v[8:9], v[6:7], 1.0
	v_fma_f64 v[6:7], v[8:9], v[6:7], 1.0
	v_cvt_i32_f64_e32 v4, v[4:5]
	v_ldexp_f64 v[4:5], v[6:7], v4
	v_mul_f64 v[4:5], v[4:5], s[4:5]
	v_cmp_nlt_f64_e32 vcc, s[10:11], v[2:3]
	v_cmp_ngt_f64_e64 s[0:1], s[16:17], v[2:3]
	v_cvt_f32_f64_e32 v47, v[50:51]
	v_cndmask_b32_e32 v5, v70, v5, vcc
	s_and_b64 vcc, s[0:1], vcc
	v_cndmask_b32_e64 v3, 0, v5, s[0:1]
	v_cndmask_b32_e32 v2, 0, v4, vcc
	v_cvt_f32_f64_e32 v64, v[2:3]
	v_cvt_f64_f32_e32 v[4:5], v64
	v_add_f64 v[52:53], v[2:3], -v[4:5]
	v_or_b32_e32 v2, 34, v40
	v_cvt_f64_u32_e32 v[2:3], v2
	v_mul_f64 v[2:3], v[2:3], s[6:7]
	v_rndne_f64_e32 v[4:5], v[2:3]
	v_add_f64 v[6:7], v[2:3], -v[4:5]
	v_mul_f64 v[8:9], v[6:7], s[12:13]
	v_fmac_f64_e32 v[8:9], s[20:21], v[6:7]
	v_fma_f64 v[6:7], s[22:23], v[8:9], v[0:1]
	v_fma_f64 v[6:7], v[8:9], v[6:7], s[24:25]
	v_fma_f64 v[6:7], v[8:9], v[6:7], s[26:27]
	v_fma_f64 v[6:7], v[8:9], v[6:7], s[28:29]
	v_fma_f64 v[6:7], v[8:9], v[6:7], s[30:31]
	v_fma_f64 v[6:7], v[8:9], v[6:7], s[34:35]
	v_fma_f64 v[6:7], v[8:9], v[6:7], s[36:37]
	v_fma_f64 v[6:7], v[8:9], v[6:7], s[38:39]
	v_fma_f64 v[6:7], v[8:9], v[6:7], s[40:41]
	v_fma_f64 v[6:7], v[8:9], v[6:7], 1.0
	v_fma_f64 v[6:7], v[8:9], v[6:7], 1.0
	v_cvt_i32_f64_e32 v4, v[4:5]
	v_ldexp_f64 v[4:5], v[6:7], v4
	v_mul_f64 v[4:5], v[4:5], s[4:5]
	v_cmp_nlt_f64_e32 vcc, s[10:11], v[2:3]
	v_cmp_ngt_f64_e64 s[0:1], s[16:17], v[2:3]
	v_cvt_f32_f64_e32 v48, v[52:53]
	v_cndmask_b32_e32 v5, v70, v5, vcc
	s_and_b64 vcc, s[0:1], vcc
	v_cndmask_b32_e64 v3, 0, v5, s[0:1]
	v_cndmask_b32_e32 v2, 0, v4, vcc
	v_cvt_f32_f64_e32 v65, v[2:3]
	v_cvt_f64_f32_e32 v[4:5], v65
	s_waitcnt vmcnt(0)
	v_add_f64 v[76:77], v[2:3], -v[4:5]
	v_or_b32_e32 v2, 35, v40
	v_cvt_f64_u32_e32 v[2:3], v2
	v_mul_f64 v[2:3], v[2:3], s[6:7]
	v_rndne_f64_e32 v[4:5], v[2:3]
	v_add_f64 v[6:7], v[2:3], -v[4:5]
	v_mul_f64 v[8:9], v[6:7], s[12:13]
	v_fmac_f64_e32 v[8:9], s[20:21], v[6:7]
	v_fma_f64 v[6:7], s[22:23], v[8:9], v[0:1]
	v_fma_f64 v[6:7], v[8:9], v[6:7], s[24:25]
	v_fma_f64 v[6:7], v[8:9], v[6:7], s[26:27]
	v_fma_f64 v[6:7], v[8:9], v[6:7], s[28:29]
	v_fma_f64 v[6:7], v[8:9], v[6:7], s[30:31]
	v_fma_f64 v[6:7], v[8:9], v[6:7], s[34:35]
	v_fma_f64 v[6:7], v[8:9], v[6:7], s[36:37]
	v_fma_f64 v[6:7], v[8:9], v[6:7], s[38:39]
	v_fma_f64 v[6:7], v[8:9], v[6:7], s[40:41]
	v_fma_f64 v[6:7], v[8:9], v[6:7], 1.0
	v_fma_f64 v[6:7], v[8:9], v[6:7], 1.0
	v_cvt_i32_f64_e32 v4, v[4:5]
	v_ldexp_f64 v[4:5], v[6:7], v4
	v_mul_f64 v[4:5], v[4:5], s[4:5]
	v_cmp_nlt_f64_e32 vcc, s[10:11], v[2:3]
	v_cmp_ngt_f64_e64 s[0:1], s[16:17], v[2:3]
	v_cvt_f32_f64_e32 v49, v[76:77]
	v_cndmask_b32_e32 v5, v70, v5, vcc
	s_and_b64 vcc, s[0:1], vcc
	v_cndmask_b32_e64 v3, 0, v5, s[0:1]
	v_cndmask_b32_e32 v2, 0, v4, vcc
	v_cvt_f32_f64_e32 v66, v[2:3]
	v_cvt_f64_f32_e32 v[4:5], v66
	v_add_f64 v[78:79], v[2:3], -v[4:5]
	v_or_b32_e32 v2, 36, v40
	v_cvt_f64_u32_e32 v[2:3], v2
	v_mul_f64 v[2:3], v[2:3], s[6:7]
	v_rndne_f64_e32 v[4:5], v[2:3]
	v_add_f64 v[6:7], v[2:3], -v[4:5]
	v_mul_f64 v[8:9], v[6:7], s[12:13]
	v_fmac_f64_e32 v[8:9], s[20:21], v[6:7]
	v_fma_f64 v[6:7], s[22:23], v[8:9], v[0:1]
	v_fma_f64 v[6:7], v[8:9], v[6:7], s[24:25]
	v_fma_f64 v[6:7], v[8:9], v[6:7], s[26:27]
	v_fma_f64 v[6:7], v[8:9], v[6:7], s[28:29]
	v_fma_f64 v[6:7], v[8:9], v[6:7], s[30:31]
	v_fma_f64 v[6:7], v[8:9], v[6:7], s[34:35]
	v_fma_f64 v[6:7], v[8:9], v[6:7], s[36:37]
	v_fma_f64 v[6:7], v[8:9], v[6:7], s[38:39]
	v_fma_f64 v[6:7], v[8:9], v[6:7], s[40:41]
	v_fma_f64 v[6:7], v[8:9], v[6:7], 1.0
	v_fma_f64 v[6:7], v[8:9], v[6:7], 1.0
	v_cvt_i32_f64_e32 v4, v[4:5]
	v_ldexp_f64 v[4:5], v[6:7], v4
	v_mul_f64 v[4:5], v[4:5], s[4:5]
	v_cmp_nlt_f64_e32 vcc, s[10:11], v[2:3]
	v_cmp_ngt_f64_e64 s[0:1], s[16:17], v[2:3]
	v_cvt_f32_f64_e32 v50, v[78:79]
	v_cndmask_b32_e32 v5, v70, v5, vcc
	s_and_b64 vcc, s[0:1], vcc
	v_cndmask_b32_e64 v3, 0, v5, s[0:1]
	v_cndmask_b32_e32 v2, 0, v4, vcc
	v_cvt_f32_f64_e32 v67, v[2:3]
	v_cvt_f64_f32_e32 v[4:5], v67
	v_add_f64 v[80:81], v[2:3], -v[4:5]
	v_or_b32_e32 v2, 37, v40
	v_cvt_f64_u32_e32 v[2:3], v2
	v_mul_f64 v[2:3], v[2:3], s[6:7]
	v_rndne_f64_e32 v[4:5], v[2:3]
	v_add_f64 v[6:7], v[2:3], -v[4:5]
	v_mul_f64 v[8:9], v[6:7], s[12:13]
	v_fmac_f64_e32 v[8:9], s[20:21], v[6:7]
	v_fma_f64 v[6:7], s[22:23], v[8:9], v[0:1]
	v_fma_f64 v[6:7], v[8:9], v[6:7], s[24:25]
	v_fma_f64 v[6:7], v[8:9], v[6:7], s[26:27]
	v_fma_f64 v[6:7], v[8:9], v[6:7], s[28:29]
	v_fma_f64 v[6:7], v[8:9], v[6:7], s[30:31]
	v_fma_f64 v[6:7], v[8:9], v[6:7], s[34:35]
	v_fma_f64 v[6:7], v[8:9], v[6:7], s[36:37]
	v_fma_f64 v[6:7], v[8:9], v[6:7], s[38:39]
	v_fma_f64 v[6:7], v[8:9], v[6:7], s[40:41]
	v_fma_f64 v[6:7], v[8:9], v[6:7], 1.0
	v_fma_f64 v[6:7], v[8:9], v[6:7], 1.0
	v_cvt_i32_f64_e32 v4, v[4:5]
	v_ldexp_f64 v[4:5], v[6:7], v4
	v_mul_f64 v[4:5], v[4:5], s[4:5]
	v_cmp_nlt_f64_e32 vcc, s[10:11], v[2:3]
	v_cmp_ngt_f64_e64 s[0:1], s[16:17], v[2:3]
	v_cvt_f32_f64_e32 v51, v[80:81]
	v_cndmask_b32_e32 v5, v70, v5, vcc
	s_and_b64 vcc, s[0:1], vcc
	v_cndmask_b32_e64 v3, 0, v5, s[0:1]
	v_cndmask_b32_e32 v2, 0, v4, vcc
	v_cvt_f32_f64_e32 v68, v[2:3]
	v_cvt_f64_f32_e32 v[4:5], v68
	v_add_f64 v[82:83], v[2:3], -v[4:5]
	v_or_b32_e32 v2, 38, v40
	v_cvt_f64_u32_e32 v[2:3], v2
	v_mul_f64 v[2:3], v[2:3], s[6:7]
	v_rndne_f64_e32 v[4:5], v[2:3]
	v_add_f64 v[6:7], v[2:3], -v[4:5]
	v_mul_f64 v[8:9], v[6:7], s[12:13]
	v_fmac_f64_e32 v[8:9], s[20:21], v[6:7]
	v_fma_f64 v[6:7], s[22:23], v[8:9], v[0:1]
	v_fma_f64 v[6:7], v[8:9], v[6:7], s[24:25]
	v_fma_f64 v[6:7], v[8:9], v[6:7], s[26:27]
	v_fma_f64 v[6:7], v[8:9], v[6:7], s[28:29]
	v_fma_f64 v[6:7], v[8:9], v[6:7], s[30:31]
	v_fma_f64 v[6:7], v[8:9], v[6:7], s[34:35]
	v_fma_f64 v[6:7], v[8:9], v[6:7], s[36:37]
	v_fma_f64 v[6:7], v[8:9], v[6:7], s[38:39]
	v_fma_f64 v[6:7], v[8:9], v[6:7], s[40:41]
	v_fma_f64 v[6:7], v[8:9], v[6:7], 1.0
	v_fma_f64 v[6:7], v[8:9], v[6:7], 1.0
	v_cvt_i32_f64_e32 v4, v[4:5]
	v_ldexp_f64 v[4:5], v[6:7], v4
	v_mul_f64 v[4:5], v[4:5], s[4:5]
	v_cmp_nlt_f64_e32 vcc, s[10:11], v[2:3]
	v_cmp_ngt_f64_e64 s[0:1], s[16:17], v[2:3]
	v_cvt_f32_f64_e32 v52, v[82:83]
	v_cndmask_b32_e32 v5, v70, v5, vcc
	s_and_b64 vcc, s[0:1], vcc
	v_cndmask_b32_e64 v3, 0, v5, s[0:1]
	v_cndmask_b32_e32 v2, 0, v4, vcc
	v_cvt_f32_f64_e32 v69, v[2:3]
	v_cvt_f64_f32_e32 v[4:5], v69
	v_add_f64 v[84:85], v[2:3], -v[4:5]
	v_or_b32_e32 v2, 39, v40
	v_cvt_f64_u32_e32 v[2:3], v2
	v_mul_f64 v[72:73], v[2:3], s[6:7]
	v_rndne_f64_e32 v[74:75], v[72:73]
	v_add_f64 v[2:3], v[72:73], -v[74:75]
	v_mul_f64 v[86:87], v[2:3], s[12:13]
	v_fmac_f64_e32 v[86:87], s[20:21], v[2:3]
	v_fmac_f64_e32 v[0:1], s[22:23], v[86:87]
	v_fma_f64 v[0:1], v[86:87], v[0:1], s[24:25]
	v_fma_f64 v[0:1], v[86:87], v[0:1], s[26:27]
	v_fma_f64 v[0:1], v[86:87], v[0:1], s[28:29]
	v_fma_f64 v[0:1], v[86:87], v[0:1], s[30:31]
	v_fma_f64 v[0:1], v[86:87], v[0:1], s[34:35]
	v_fma_f64 v[0:1], v[86:87], v[0:1], s[36:37]
	v_fma_f64 v[0:1], v[86:87], v[0:1], s[38:39]
	s_lshl_b32 s26, s60, 4
	v_fma_f64 v[0:1], v[86:87], v[0:1], s[40:41]
	s_and_b32 s0, s26, 0xffffff80
	v_fma_f64 v[88:89], v[86:87], v[0:1], 1.0
	v_add_u32_e32 v2, s0, v54
	v_mov_b64_e32 v[0:1], s[14:15]
	v_mad_i64_i32 v[0:1], s[0:1], v2, s2, v[0:1]
	v_lshl_add_u64 v[0:1], v[0:1], 0, s[18:19]
	v_lshl_add_u64 v[0:1], v[40:41], 1, v[0:1]
	s_movk_i32 s0, 0x1000
	v_add_co_u32_e32 v92, vcc, s0, v0
	v_fma_f64 v[86:87], v[86:87], v[88:89], 1.0
	s_nop 0
	v_addc_co_u32_e32 v93, vcc, 0, v1, vcc
	v_add_co_u32_e32 v94, vcc, s3, v0
	v_cvt_i32_f64_e32 v71, v[74:75]
	s_nop 0
	v_addc_co_u32_e32 v95, vcc, 0, v1, vcc
	global_load_dwordx4 v[0:3], v[92:93], off offset:2048
	global_load_dwordx4 v[4:7], v[92:93], off offset:2112
	global_load_dwordx4 v[8:11], v[94:95], off
	global_load_dwordx4 v[12:15], v[94:95], off offset:64
	global_load_dwordx4 v[16:19], v[92:93], off offset:2176
	global_load_dwordx4 v[20:23], v[92:93], off offset:2240
	global_load_dwordx4 v[24:27], v[94:95], off offset:128
	global_load_dwordx4 v[28:31], v[94:95], off offset:192
	v_ldexp_f64 v[74:75], v[86:87], v71
	v_mul_f64 v[74:75], v[74:75], s[4:5]
	v_cmp_nlt_f64_e32 vcc, s[10:11], v[72:73]
	v_cmp_ngt_f64_e64 s[0:1], s[16:17], v[72:73]
	v_cvt_f32_f64_e32 v71, v[32:33]
	v_cndmask_b32_e32 v70, v70, v75, vcc
	s_and_b64 vcc, s[0:1], vcc
	v_cndmask_b32_e64 v73, 0, v70, s[0:1]
	v_cndmask_b32_e32 v72, 0, v74, vcc
	v_cvt_f32_f64_e32 v70, v[72:73]
	v_sub_u32_e32 v32, 0x7f, v54
	s_movk_i32 s0, 0x110
	v_cvt_f64_f32_e32 v[74:75], v70
	v_cvt_f32_i32_e32 v77, v32
	v_mul_lo_u32 v32, v54, s0
	s_movk_i32 s0, 0x440
	v_readlane_b32 s4, v251, 0
	v_add_f64 v[86:87], v[72:73], -v[74:75]
	v_cvt_f32_f64_e32 v72, v[34:35]
	v_add_u32_e32 v34, 0, v32
	v_mad_u32_u24 v32, v108, s0, v54
	s_movk_i32 s0, 0x88
	s_lshr_b32 s4, s4, 1
	v_lshl_add_u32 v78, v32, 1, 0
	v_mad_i32_i24 v32, v90, s0, v54
	s_lshl_b64 s[0:1], s[60:61], 15
	s_and_b32 s4, s4, 0x7fffffe0
	s_add_u32 s0, s4, s0
	v_and_b32_e32 v35, 48, v129
	v_lshl_add_u32 v79, v32, 1, 0
	v_lshlrev_b32_e32 v32, 8, v91
	v_mov_b32_e32 v33, v41
	s_addc_u32 s1, 0, s1
	v_cvt_f32_f64_e32 v74, v[38:39]
	v_lshl_add_u64 v[32:33], s[0:1], 0, v[32:33]
	v_lshrrev_b32_e32 v38, 1, v35
	v_or_b32_e32 v32, v32, v38
	v_cvt_f32_f64_e32 v73, v[36:37]
	v_add_u32_e32 v36, 0, v35
	v_mul_u32_u24_e32 v37, 0x110, v91
	v_lshl_add_u64 v[32:33], s[92:93], 0, v[32:33]
	s_mov_b64 s[0:1], 0xb200000
	s_ashr_i32 s97, s96, 31
	s_add_i32 s4, s60, s96
	v_cvt_f32_f64_e32 v75, v[42:43]
	v_cvt_f32_f64_e32 v53, v[84:85]
	v_cvt_f32_f64_e32 v76, v[86:87]
	v_lshl_add_u64 v[42:43], v[32:33], 0, s[0:1]
	s_lshl_b64 s[0:1], s[96:97], 15
	s_lshl_b32 s10, s96, 4
	s_lshl_b32 s11, s4, 7
	s_lshl_b32 s12, s96, 7
	s_mov_b32 s13, 0xc2fc0000
	s_mov_b32 s16, 0x3f2aaaab
	v_mov_b32_e32 v80, 0x3ecc95a3
	s_mov_b32 s17, 0x3f317218
	s_mov_b32 s20, 0x33800000
	s_mov_b32 s21, 0xffff0000
	v_add_u32_e32 v81, v34, v35
	v_add_u32_e32 v82, v36, v37
	s_movk_i32 s22, 0x7fff
	s_movk_i32 s23, 0x4000
	s_movk_i32 s24, 0x6000
	v_mov_b32_e32 v83, 0x42800000
	v_mov_b32_e32 v84, 0x7fc00000
	v_mov_b32_e32 v85, 0xff800000
	s_mov_b32 s25, s60
	s_waitcnt vmcnt(0)
	s_branch .LBB0_272

.LBB0_272:
	s_and_b32 s4, s25, 7
	v_cvt_f32_ubyte0_e32 v32, s4
	v_sub_f32_e32 v32, 0xc0a00000, v32
	v_cmp_gt_f32_e32 vcc, s13, v32
	s_and_b32 s6, s26, 0xffffff80
	s_and_b64 s[4:5], vcc, exec
	v_cndmask_b32_e32 v33, 0, v83, vcc
	v_add_f32_e32 v32, v32, v33
	v_exp_f32_e32 v32, v32
	s_cselect_b32 s4, 0xffffffc0, 0
	s_waitcnt vmcnt(8)
	v_lshlrev_b32_e32 v98, 16, v16
	v_lshlrev_b32_e32 v96, 16, v0
	v_ldexp_f32 v34, v32, s4
	v_sub_f32_e32 v35, 1.0, v34
	v_add_f32_e32 v32, -1.0, v35
	v_sub_f32_e32 v33, v32, v35
	v_add_f32_e32 v33, 1.0, v33
	v_sub_f32_e64 v32, -v34, v32
	v_add_f32_e32 v36, v32, v33
	v_frexp_mant_f32_e32 v37, v35
	v_cvt_f64_f32_e32 v[32:33], v35
	v_frexp_exp_i32_f64_e32 v32, v[32:33]
	v_cmp_gt_f32_e32 vcc, s16, v37
	v_and_b32_e32 v99, 0xffff0000, v16
	v_and_b32_e32 v97, 0xffff0000, v0
	v_subbrev_co_u32_e32 v32, vcc, 0, v32, vcc
	v_sub_u32_e32 v33, 0, v32
	v_ldexp_f32 v35, v35, v33
	v_ldexp_f32 v33, v36, v33
	v_add_f32_e32 v36, -1.0, v35
	v_add_f32_e32 v39, 1.0, v35
	v_add_f32_e32 v37, 1.0, v36
	v_add_f32_e32 v86, -1.0, v39
	v_sub_f32_e32 v37, v35, v37
	v_sub_f32_e32 v35, v35, v86
	v_add_f32_e32 v37, v33, v37
	v_add_f32_e32 v33, v33, v35
	v_add_f32_e32 v35, v39, v33
	v_rcp_f32_e32 v86, v35
	v_add_f32_e32 v38, v36, v37
	v_sub_f32_e32 v36, v38, v36
	v_sub_f32_e32 v36, v37, v36
	v_sub_f32_e32 v37, v35, v39
	v_sub_f32_e32 v33, v33, v37
	v_mul_f32_e32 v37, v38, v86
	v_mul_f32_e32 v39, v35, v37
	v_fma_f32 v87, v37, v35, -v39
	v_fmac_f32_e32 v87, v37, v33
	v_add_f32_e32 v88, v39, v87
	v_sub_f32_e32 v89, v38, v88
	v_sub_f32_e32 v38, v38, v89
	v_sub_f32_e32 v39, v88, v39
	v_sub_f32_e32 v38, v38, v88
	v_add_f32_e32 v36, v36, v38
	v_sub_f32_e32 v38, v39, v87
	v_add_f32_e32 v36, v38, v36
	v_add_f32_e32 v38, v89, v36
	v_mul_f32_e32 v39, v86, v38
	v_mul_f32_e32 v87, v35, v39
	v_fma_f32 v35, v39, v35, -v87
	v_fmac_f32_e32 v35, v39, v33
	v_sub_f32_e32 v33, v89, v38
	v_add_f32_e32 v33, v36, v33
	v_add_f32_e32 v36, v87, v35
	v_sub_f32_e32 v88, v38, v36
	v_sub_f32_e32 v38, v38, v88
	v_sub_f32_e32 v87, v36, v87
	v_sub_f32_e32 v36, v38, v36
	v_add_f32_e32 v33, v33, v36
	v_sub_f32_e32 v35, v87, v35
	v_cvt_f32_i32_e32 v32, v32
	v_add_f32_e32 v33, v35, v33
	v_add_f32_e32 v35, v37, v39
	v_add_f32_e32 v33, v88, v33
	v_sub_f32_e32 v36, v35, v37
	v_mul_f32_e32 v33, v86, v33
	v_sub_f32_e32 v36, v39, v36
	v_add_f32_e32 v33, v36, v33
	v_mul_f32_e32 v39, 0x3f317218, v32
	v_add_f32_e32 v36, v35, v33
	v_fma_f32 v86, v32, s17, -v39
	v_mul_f32_e32 v37, v36, v36
	v_fmac_f32_e32 v86, 0xb102e308, v32
	v_sub_f32_e32 v32, v36, v35
	v_fmamk_f32 v38, v37, 0x3e9b6dac, v80
	v_sub_f32_e32 v32, v33, v32
	v_add_f32_e32 v33, v39, v86
	v_fmaak_f32 v38, v37, v38, 0x3f2aaada
	v_sub_f32_e32 v35, v33, v39
	v_ldexp_f32 v39, v36, 1
	v_mul_f32_e32 v36, v36, v37
	v_mul_f32_e32 v36, v36, v38
	v_add_f32_e32 v37, v39, v36
	v_sub_f32_e32 v38, v37, v39
	v_ldexp_f32 v32, v32, 1
	v_sub_f32_e32 v36, v36, v38
	v_add_f32_e32 v32, v32, v36
	v_add_f32_e32 v36, v37, v32
	v_sub_f32_e32 v37, v36, v37
	v_sub_f32_e32 v32, v32, v37
	v_add_f32_e32 v37, v33, v36
	v_sub_f32_e32 v38, v37, v33
	v_sub_f32_e32 v39, v37, v38
	v_sub_f32_e32 v35, v86, v35
	v_sub_f32_e32 v33, v33, v39
	v_sub_f32_e32 v36, v36, v38
	v_add_f32_e32 v33, v36, v33
	v_add_f32_e32 v36, v35, v32
	v_sub_f32_e32 v38, v36, v35
	v_sub_f32_e32 v39, v36, v38
	v_sub_f32_e32 v35, v35, v39
	v_sub_f32_e32 v32, v32, v38
	v_add_f32_e32 v33, v36, v33
	v_add_f32_e32 v32, v32, v35
	v_add_f32_e32 v35, v37, v33
	v_sub_f32_e32 v36, v35, v37
	v_sub_f32_e32 v33, v33, v36
	v_add_f32_e32 v32, v32, v33
	v_add_u32_e32 v33, s6, v54
	v_cvt_f32_i32_e32 v33, v33
	v_add_f32_e32 v32, v35, v32
	v_cmp_nlt_f32_e32 vcc, 1.0, v34
	v_lshlrev_b32_e32 v102, 16, v17
	v_mul_f32_e32 v36, v56, v33
	v_cndmask_b32_e32 v32, v84, v32, vcc
	v_cmp_neq_f32_e32 vcc, 1.0, v34
	v_fract_f32_e32 v37, v36
	v_fma_f32 v36, v33, v56, -v36
	v_cndmask_b32_e32 v32, v85, v32, vcc
	v_cmp_gt_f32_e32 vcc, s20, v34
	v_fmac_f32_e32 v36, v72, v33
	v_mul_f32_e32 v38, v57, v33
	v_cndmask_b32_e64 v32, v32, -v34, vcc
	v_mul_f32_e32 v34, v55, v33
	v_fract_f32_e32 v35, v34
	v_fma_f32 v34, v33, v55, -v34
	v_fmac_f32_e32 v34, v71, v33
	v_add_f32_e32 v34, v35, v34
	v_sin_f32_e32 v35, v34
	v_cos_f32_e32 v34, v34
	v_add_f32_e32 v36, v37, v36
	v_fract_f32_e32 v39, v38
	v_fma_f32 v38, v33, v57, -v38
	v_sin_f32_e32 v37, v36
	v_fmac_f32_e32 v38, v73, v33
	v_mul_f32_e32 v86, v58, v33
	v_cos_f32_e32 v36, v36
	v_add_f32_e32 v38, v39, v38
	v_fract_f32_e32 v87, v86
	v_fma_f32 v86, v33, v58, -v86
	v_sin_f32_e32 v39, v38
	v_fmac_f32_e32 v86, v74, v33
	v_mul_f32_e32 v88, v59, v33
	v_mul_f32_e32 v112, v35, v98
	v_cos_f32_e32 v38, v38
	v_add_f32_e32 v86, v87, v86
	v_fract_f32_e32 v89, v88
	v_fma_f32 v88, v33, v59, -v88
	v_fma_f32 v112, v34, v96, -v112
	v_mul_f32_e32 v34, v34, v98
	v_sin_f32_e32 v87, v86
	v_fmac_f32_e32 v88, v75, v33
	v_mul_f32_e32 v90, v60, v33
	v_fmac_f32_e32 v34, v35, v96
	v_mul_f32_e32 v35, v37, v99
	v_cos_f32_e32 v86, v86
	v_add_f32_e32 v88, v89, v88
	v_fract_f32_e32 v91, v90
	v_fma_f32 v90, v33, v60, -v90
	v_fma_f32 v35, v36, v97, -v35
	v_mul_f32_e32 v36, v36, v99
	v_sin_f32_e32 v89, v88
	v_fmac_f32_e32 v90, v44, v33
	v_mul_f32_e32 v92, v61, v33
	v_lshlrev_b32_e32 v100, 16, v1
	v_fmac_f32_e32 v36, v37, v97
	v_mul_f32_e32 v37, v39, v102
	v_cos_f32_e32 v88, v88
	v_add_f32_e32 v90, v91, v90
	v_fract_f32_e32 v93, v92
	v_fma_f32 v92, v33, v61, -v92
	v_and_b32_e32 v103, 0xffff0000, v17
	v_fma_f32 v37, v38, v100, -v37
	v_mul_f32_e32 v38, v38, v102
	v_sin_f32_e32 v91, v90
	v_fmac_f32_e32 v92, v45, v33
	v_mul_f32_e32 v94, v62, v33
	v_and_b32_e32 v101, 0xffff0000, v1
	v_fmac_f32_e32 v38, v39, v100
	v_mul_f32_e32 v39, v87, v103
	v_cos_f32_e32 v90, v90
	v_add_f32_e32 v92, v93, v92
	v_fract_f32_e32 v95, v94
	v_fma_f32 v94, v33, v62, -v94
	v_lshlrev_b32_e32 v106, 16, v18
	v_fma_f32 v39, v86, v101, -v39
	v_mul_f32_e32 v86, v86, v103
	v_sin_f32_e32 v93, v92
	v_fmac_f32_e32 v94, v46, v33
	v_lshlrev_b32_e32 v104, 16, v2
	v_fmac_f32_e32 v86, v87, v101
	v_mul_f32_e32 v87, v89, v106
	v_cos_f32_e32 v92, v92
	v_add_f32_e32 v94, v95, v94
	v_and_b32_e32 v107, 0xffff0000, v18
	v_fma_f32 v87, v88, v104, -v87
	v_mul_f32_e32 v88, v88, v106
	v_sin_f32_e32 v95, v94
	v_and_b32_e32 v105, 0xffff0000, v2
	v_fmac_f32_e32 v88, v89, v104
	v_mul_f32_e32 v89, v91, v107
	v_cos_f32_e32 v94, v94
	v_lshlrev_b32_e32 v110, 16, v19
	v_fma_f32 v89, v90, v105, -v89
	v_mul_f32_e32 v90, v90, v107
	v_lshlrev_b32_e32 v108, 16, v3
	v_mul_f32_e32 v34, 0x3db504f3, v34
	v_mul_f32_e32 v35, 0x3db504f3, v35
	v_mul_f32_e32 v36, 0x3db504f3, v36
	v_mul_f32_e32 v37, 0x3db504f3, v37
	v_mul_f32_e32 v38, 0x3db504f3, v38
	v_mul_f32_e32 v39, 0x3db504f3, v39
	v_mul_f32_e32 v88, 0x3db504f3, v88
	v_fmac_f32_e32 v90, v91, v105
	v_mul_f32_e32 v91, v93, v110
	v_and_b32_e32 v111, 0xffff0000, v19
	v_mul_f32_e32 v112, 0x3db504f3, v112
	v_mul_f32_e32 v86, 0x3db504f3, v86
	v_mul_f32_e32 v87, 0x3db504f3, v87
	v_mul_f32_e32 v89, 0x3db504f3, v89
	v_mul_f32_e32 v90, 0x3db504f3, v90
	v_fma_f32 v91, v92, v108, -v91
	v_mul_f32_e32 v92, v92, v110
	v_cvt_pk_bf16_f32 v35, v112, v35
	v_cvt_pk_bf16_f32 v34, v34, v36
	v_cvt_pk_bf16_f32 v36, v37, v39
	v_cvt_pk_bf16_f32 v37, v38, v86
	v_cvt_pk_bf16_f32 v38, v87, v89
	v_cvt_pk_bf16_f32 v39, v88, v90
	v_mul_f32_e32 v88, v63, v33
	v_and_b32_e32 v109, 0xffff0000, v3
	v_fmac_f32_e32 v92, v93, v108
	v_mul_f32_e32 v93, v95, v111
	v_fract_f32_e32 v89, v88
	v_fma_f32 v88, v33, v63, -v88
	v_mul_f32_e32 v91, 0x3db504f3, v91
	v_fma_f32 v93, v94, v109, -v93
	v_mul_f32_e32 v94, v94, v111
	v_fmac_f32_e32 v88, v47, v33
	v_mul_f32_e32 v90, v64, v33
	v_mul_f32_e32 v92, 0x3db504f3, v92
	v_mul_f32_e32 v93, 0x3db504f3, v93
	v_fmac_f32_e32 v94, v95, v109
	v_cvt_pk_bf16_f32 v86, v91, v93
	v_add_f32_e32 v88, v89, v88
	v_fract_f32_e32 v91, v90
	v_fma_f32 v90, v33, v64, -v90
	v_mul_f32_e32 v94, 0x3db504f3, v94
	v_cvt_pk_bf16_f32 v87, v92, v94
	v_sin_f32_e32 v89, v88
	v_fmac_f32_e32 v90, v48, v33
	v_mul_f32_e32 v92, v65, v33
	v_cos_f32_e32 v88, v88
	v_add_f32_e32 v90, v91, v90
	v_fract_f32_e32 v93, v92
	v_fma_f32 v92, v33, v65, -v92
	v_mul_f32_e32 v102, v70, v33
	v_sin_f32_e32 v91, v90
	v_fmac_f32_e32 v92, v49, v33
	v_mul_f32_e32 v94, v66, v33
	v_mul_f32_e32 v96, v67, v33
	v_mul_f32_e32 v98, v68, v33
	v_mul_f32_e32 v100, v69, v33
	v_fract_f32_e32 v103, v102
	v_fma_f32 v102, v33, v70, -v102
	v_cos_f32_e32 v90, v90
	v_add_f32_e32 v92, v93, v92
	v_fract_f32_e32 v95, v94
	v_fma_f32 v94, v33, v66, -v94
	v_fract_f32_e32 v97, v96
	v_fma_f32 v96, v33, v67, -v96
	v_fract_f32_e32 v99, v98
	v_fma_f32 v98, v33, v68, -v98
	v_fract_f32_e32 v101, v100
	v_fma_f32 v100, v33, v69, -v100
	v_fmac_f32_e32 v102, v76, v33
	v_lshlrev_b32_e32 v105, 16, v20
	v_sin_f32_e32 v93, v92
	v_fmac_f32_e32 v94, v50, v33
	v_fmac_f32_e32 v96, v51, v33
	v_fmac_f32_e32 v98, v52, v33
	v_fmac_f32_e32 v100, v53, v33
	v_add_f32_e32 v33, v103, v102
	v_lshlrev_b32_e32 v103, 16, v4
	v_mul_f32_e32 v119, v89, v105
	v_cos_f32_e32 v92, v92
	v_add_f32_e32 v94, v95, v94
	v_and_b32_e32 v106, 0xffff0000, v20
	v_fma_f32 v119, v88, v103, -v119
	v_mul_f32_e32 v88, v88, v105
	v_sin_f32_e32 v95, v94
	v_and_b32_e32 v104, 0xffff0000, v4
	v_fmac_f32_e32 v88, v89, v103
	v_mul_f32_e32 v89, v91, v106
	v_cos_f32_e32 v94, v94
	v_add_f32_e32 v96, v97, v96
	v_lshlrev_b32_e32 v109, 16, v21
	v_fma_f32 v89, v90, v104, -v89
	v_mul_f32_e32 v90, v90, v106
	v_sin_f32_e32 v97, v96
	v_lshlrev_b32_e32 v107, 16, v5
	v_fmac_f32_e32 v90, v91, v104
	v_mul_f32_e32 v91, v93, v109
	v_cos_f32_e32 v96, v96
	v_add_f32_e32 v98, v99, v98
	v_and_b32_e32 v110, 0xffff0000, v21
	v_fma_f32 v91, v92, v107, -v91
	v_mul_f32_e32 v92, v92, v109
	v_sin_f32_e32 v99, v98
	v_and_b32_e32 v108, 0xffff0000, v5
	v_fmac_f32_e32 v92, v93, v107
	v_mul_f32_e32 v93, v95, v110
	v_cos_f32_e32 v98, v98
	v_add_f32_e32 v100, v101, v100
	v_lshlrev_b32_e32 v113, 16, v22
	v_fma_f32 v93, v94, v108, -v93
	v_mul_f32_e32 v94, v94, v110
	v_sin_f32_e32 v101, v100
	v_lshlrev_b32_e32 v111, 16, v6
	v_fmac_f32_e32 v94, v95, v108
	v_mul_f32_e32 v95, v97, v113
	v_cos_f32_e32 v100, v100
	v_and_b32_e32 v114, 0xffff0000, v22
	v_fma_f32 v95, v96, v111, -v95
	v_mul_f32_e32 v96, v96, v113
	v_sin_f32_e32 v102, v33
	v_and_b32_e32 v112, 0xffff0000, v6
	v_fmac_f32_e32 v96, v97, v111
	v_mul_f32_e32 v97, v99, v114
	v_cos_f32_e32 v33, v33
	v_lshlrev_b32_e32 v117, 16, v23
	v_fma_f32 v97, v98, v112, -v97
	v_mul_f32_e32 v98, v98, v114
	v_lshlrev_b32_e32 v115, 16, v7
	v_fmac_f32_e32 v98, v99, v112
	v_mul_f32_e32 v99, v101, v117
	v_mul_f32_e32 v32, 0x3fb8aa3b, v32
	v_and_b32_e32 v118, 0xffff0000, v23
	v_fma_f32 v99, v100, v115, -v99
	v_mul_f32_e32 v100, v100, v117
	v_and_b32_e32 v116, 0xffff0000, v7
	v_fmac_f32_e32 v100, v101, v115
	v_mul_f32_e32 v101, v102, v118
	v_mul_f32_e32 v32, v32, v77
	v_fma_f32 v101, v33, v116, -v101
	v_mul_f32_e32 v33, v33, v118
	v_exp_f32_e32 v32, v32
	v_fmac_f32_e32 v33, v102, v116
	v_mul_f32_e32 v88, 0x3db504f3, v88
	v_mul_f32_e32 v89, 0x3db504f3, v89
	v_mul_f32_e32 v90, 0x3db504f3, v90
	v_mul_f32_e32 v91, 0x3db504f3, v91
	v_mul_f32_e32 v92, 0x3db504f3, v92
	v_mul_f32_e32 v93, 0x3db504f3, v93
	v_mul_f32_e32 v94, 0x3db504f3, v94
	v_mul_f32_e32 v33, 0x3db504f3, v33
	v_mul_f32_e32 v119, 0x3db504f3, v119
	v_mul_f32_e32 v95, 0x3db504f3, v95
	v_mul_f32_e32 v96, 0x3db504f3, v96
	v_mul_f32_e32 v97, 0x3db504f3, v97
	v_mul_f32_e32 v98, 0x3db504f3, v98
	v_mul_f32_e32 v99, 0x3db504f3, v99
	v_mul_f32_e32 v100, 0x3db504f3, v100
	v_mul_f32_e32 v101, 0x3db504f3, v101
	v_cvt_pk_bf16_f32 v89, v119, v89
	v_cvt_pk_bf16_f32 v88, v88, v90
	v_cvt_pk_bf16_f32 v90, v91, v93
	v_cvt_pk_bf16_f32 v91, v92, v94
	v_cvt_pk_bf16_f32 v92, v95, v97
	v_cvt_pk_bf16_f32 v93, v96, v98
	v_cvt_pk_bf16_f32 v94, v99, v101
	v_cvt_pk_bf16_f32 v33, v100, v33
	ds_write_b16 v78, v35
	ds_write_b16_d16_hi v78, v35 offset:272
	v_lshlrev_b32_e32 v35, 16, v8
	v_mul_f32_e32 v35, v32, v35
	v_and_b32_e32 v95, 0xffff0000, v8
	v_mul_f32_e32 v95, v32, v95
	v_cvt_pk_bf16_f32 v35, v35, v95
	ds_write_b16 v78, v35 offset:34816
	ds_write_b16_d16_hi v78, v35 offset:35088
	ds_write_b16 v78, v36 offset:544
	ds_write_b16_d16_hi v78, v36 offset:816
	v_lshlrev_b32_e32 v35, 16, v9
	v_mul_f32_e32 v35, v32, v35
	v_and_b32_e32 v36, 0xffff0000, v9
	v_mul_f32_e32 v36, v32, v36
	v_cvt_pk_bf16_f32 v35, v35, v36
	ds_write_b16 v78, v35 offset:35360
	ds_write_b16_d16_hi v78, v35 offset:35632
	ds_write_b16 v78, v38 offset:1088
	ds_write_b16_d16_hi v78, v38 offset:1360
	v_lshlrev_b32_e32 v35, 16, v10
	v_mul_f32_e32 v35, v32, v35
	v_and_b32_e32 v36, 0xffff0000, v10
	v_mul_f32_e32 v36, v32, v36
	v_cvt_pk_bf16_f32 v35, v35, v36
	ds_write_b16 v78, v35 offset:35904
	ds_write_b16_d16_hi v78, v35 offset:36176
	ds_write_b16 v78, v86 offset:1632
	ds_write_b16_d16_hi v78, v86 offset:1904
	v_lshlrev_b32_e32 v35, 16, v11
	v_mul_f32_e32 v35, v32, v35
	v_and_b32_e32 v36, 0xffff0000, v11
	v_mul_f32_e32 v36, v32, v36
	v_cvt_pk_bf16_f32 v35, v35, v36
	ds_write_b16 v78, v35 offset:36448
	ds_write_b16_d16_hi v78, v35 offset:36720
	ds_write_b16 v79, v89
	ds_write_b16_d16_hi v79, v89 offset:272
	v_lshlrev_b32_e32 v35, 16, v12
	v_mul_f32_e32 v35, v32, v35
	v_and_b32_e32 v36, 0xffff0000, v12
	v_mul_f32_e32 v36, v32, v36
	v_cvt_pk_bf16_f32 v35, v35, v36
	ds_write_b16 v79, v35 offset:34816
	ds_write_b16_d16_hi v79, v35 offset:35088
	ds_write_b16 v78, v90 offset:9248
	ds_write_b16_d16_hi v78, v90 offset:9520
	v_lshlrev_b32_e32 v35, 16, v13
	v_mul_f32_e32 v35, v32, v35
	v_and_b32_e32 v36, 0xffff0000, v13
	v_mul_f32_e32 v36, v32, v36
	v_cvt_pk_bf16_f32 v35, v35, v36
	ds_write_b16 v78, v35 offset:44064
	ds_write_b16_d16_hi v78, v35 offset:44336
	ds_write_b16 v78, v92 offset:9792
	ds_write_b16_d16_hi v78, v92 offset:10064
	v_lshlrev_b32_e32 v35, 16, v14
	v_mul_f32_e32 v35, v32, v35
	v_and_b32_e32 v36, 0xffff0000, v14
	v_mul_f32_e32 v36, v32, v36
	v_cvt_pk_bf16_f32 v35, v35, v36
	ds_write_b16 v78, v35 offset:44608
	ds_write_b16_d16_hi v78, v35 offset:44880
	ds_write_b16 v78, v94 offset:10336
	ds_write_b16_d16_hi v78, v94 offset:10608
	v_lshlrev_b32_e32 v35, 16, v15
	v_mul_f32_e32 v35, v32, v35
	v_and_b32_e32 v36, 0xffff0000, v15
	v_mul_f32_e32 v36, v32, v36
	v_cvt_pk_bf16_f32 v35, v35, v36
	ds_write_b16 v78, v35 offset:45152
	ds_write_b16_d16_hi v78, v35 offset:45424
	ds_write_b16 v78, v34 offset:17408
	ds_write_b16_d16_hi v78, v34 offset:17680
	v_lshlrev_b32_e32 v34, 16, v24
	v_mul_f32_e32 v34, v32, v34
	v_and_b32_e32 v35, 0xffff0000, v24
	v_mul_f32_e32 v35, v32, v35
	v_cvt_pk_bf16_f32 v34, v34, v35
	ds_write_b16 v78, v34 offset:52224
	ds_write_b16_d16_hi v78, v34 offset:52496
	ds_write_b16 v78, v37 offset:17952
	ds_write_b16_d16_hi v78, v37 offset:18224
	v_lshlrev_b32_e32 v34, 16, v25
	v_mul_f32_e32 v34, v32, v34
	v_and_b32_e32 v35, 0xffff0000, v25
	v_mul_f32_e32 v35, v32, v35
	v_cvt_pk_bf16_f32 v34, v34, v35
	ds_write_b16 v78, v34 offset:52768
	ds_write_b16_d16_hi v78, v34 offset:53040
	ds_write_b16 v78, v39 offset:18496
	ds_write_b16_d16_hi v78, v39 offset:18768
	v_lshlrev_b32_e32 v34, 16, v26
	v_mul_f32_e32 v34, v32, v34
	v_and_b32_e32 v35, 0xffff0000, v26
	v_mul_f32_e32 v35, v32, v35
	v_cvt_pk_bf16_f32 v34, v34, v35
	ds_write_b16 v78, v34 offset:53312
	ds_write_b16_d16_hi v78, v34 offset:53584
	ds_write_b16 v78, v87 offset:19040
	ds_write_b16_d16_hi v78, v87 offset:19312
	v_lshlrev_b32_e32 v34, 16, v27
	v_mul_f32_e32 v34, v32, v34
	v_and_b32_e32 v35, 0xffff0000, v27
	v_mul_f32_e32 v35, v32, v35
	v_cvt_pk_bf16_f32 v34, v34, v35
	ds_write_b16 v78, v34 offset:53856
	ds_write_b16_d16_hi v78, v34 offset:54128
	ds_write_b16 v78, v88 offset:26112
	ds_write_b16_d16_hi v78, v88 offset:26384
	v_lshlrev_b32_e32 v34, 16, v28
	v_mul_f32_e32 v34, v32, v34
	v_and_b32_e32 v35, 0xffff0000, v28
	v_mul_f32_e32 v35, v32, v35
	v_cvt_pk_bf16_f32 v34, v34, v35
	ds_write_b16 v78, v34 offset:60928
	ds_write_b16_d16_hi v78, v34 offset:61200
	ds_write_b16 v78, v91 offset:26656
	ds_write_b16_d16_hi v78, v91 offset:26928
	v_lshlrev_b32_e32 v34, 16, v29
	v_mul_f32_e32 v34, v32, v34
	v_and_b32_e32 v35, 0xffff0000, v29
	v_mul_f32_e32 v35, v32, v35
	v_cvt_pk_bf16_f32 v34, v34, v35
	ds_write_b16 v78, v34 offset:61472
	ds_write_b16_d16_hi v78, v34 offset:61744
	ds_write_b16 v78, v93 offset:27200
	ds_write_b16_d16_hi v78, v93 offset:27472
	v_lshlrev_b32_e32 v34, 16, v30
	v_mul_f32_e32 v34, v32, v34
	v_and_b32_e32 v35, 0xffff0000, v30
	v_mul_f32_e32 v35, v32, v35
	v_cvt_pk_bf16_f32 v34, v34, v35
	ds_write_b16 v78, v34 offset:62016
	ds_write_b16_d16_hi v78, v34 offset:62288
	ds_write_b16 v78, v33 offset:27744
	ds_write_b16_d16_hi v78, v33 offset:28016
	v_lshlrev_b32_e32 v33, 16, v31
	v_and_b32_e32 v34, 0xffff0000, v31
	s_add_i32 s25, s25, s96
	v_mul_f32_e32 v33, v32, v33
	v_mul_f32_e32 v32, v32, v34
	s_cmpk_gt_i32 s25, 0x1ff
	v_cvt_pk_bf16_f32 v32, v33, v32
	s_cselect_b64 s[4:5], -1, 0
	s_cmpk_lt_i32 s25, 0x200
	s_mov_b64 s[6:7], -1
	ds_write_b16 v78, v32 offset:62560
	ds_write_b16_d16_hi v78, v32 offset:62832
	s_waitcnt lgkmcnt(0)
	s_barrier
	s_cbranch_scc1 .LBB0_274
	s_add_i32 s27, s26, s10
	s_mov_b64 s[6:7], 0
